# v92 + phase-8 chunk-state scan: final f32 state written through an LDS transpose as 16-byte pieces (64 B per output row) instead of 8 scattered 4-byte stores per thread
# speedup vs baseline: 1.0395x; 1.0020x over previous
; DI void unpack8(const u32x4 w, float (&f)[8]) { f[0] = bflo(w.x); f[1] = bfhi(w.x); f[2] = bflo(w.y); f[3] = bfhi(w.y); f[4] = bflo(w.z); f[5] = bfhi(w.z); f[6] = bflo(w.w); f[7] = bfhi(w.w); }
; DI u32x4 pack8(const float (&f)[8]) { u32x4 w; w.x = pk2(f[0], f[1]); w.y = pk2(f[2], f[3]); w.z = pk2(f[4], f[5]); w.w = pk2(f[6], f[7]); return w; }
; DI float ret_log2g(int h) { return log2f(1.0f - exp2f(-5.0f - (float)h)); }
; DI void phase8(const Params& p, LAS unsigned char* lds) {
;     ...
;     for (int it = blockIdx.x * NTHREADS + tid; it < 16 * 8192; it += G * NTHREADS) {
;         const int bh = it >> 13, e = (it & 8191) * 8, dv = e >> 8, dk0 = e & 255;
;         const float g256 = exp2f(256.0f * ret_log2g(bh & 3));
;         float s[8];
; #pragma unroll
;         for (int k = 0; k < 8; ++k) s[k] = 0.f;
; #pragma unroll
;         for (int c = 0; c < 16; ++c) {
;             const size_t u = (size_t)(bh * 16 + c);
;             float kv[8]; unpack8(__builtin_nontemporal_load((const u32x4*)(KVC + u * 65536 + e)), kv);
;             *(u32x4*)(BSV + (u * 256 + dv) * 512 + dk0) = pack8(s);
; #pragma unroll
;             for (int k = 0; k < 8; ++k) s[k] = g256 * s[k] + kv[k];
;         }
.LBB0_1953:
	v_add_u32_e32 v32, s80, v148
	s_mov_b32 s0, 0x20000
	v_cmp_gt_i32_e32 vcc, s0, v32
	s_and_saveexec_b64 s[0:1], vcc
	s_cbranch_execz .LBB0_1956
	v_ashrrev_i32_e32 v13, 13, v32
	v_and_b32_e32 v14, 0x1fff, v32
	v_lshrrev_b32_e32 v15, 5, v14
	v_and_b32_e32 v14, 31, v14
	v_lshlrev_b32_e32 v9, 21, v13
	v_lshl_add_u32 v9, v15, 9, v9
	v_lshl_add_u32 v9, v14, 4, v9
	v_lshlrev_b32_e32 v10, 22, v13
	v_lshl_add_u32 v10, v15, 10, v10
	v_lshl_add_u32 v10, v14, 4, v10
	v_lshlrev_b32_e32 v11, 18, v13
	v_lshl_add_u32 v11, v14, 13, v11
	v_lshl_add_u32 v11, v15, 2, v11
	v_add_u32_e32 v12, 0x1000, v11
	s_add_u32 s12, s26, 0x1f400000
	s_addc_u32 s13, s27, 0
	global_load_dwordx4 v[24:27], v9, s[12:13] nt
	s_add_u32 s12, s12, 0x20000
	s_addc_u32 s13, s13, 0
	global_load_dwordx4 v[28:31], v9, s[12:13] nt
	s_add_u32 s12, s12, 0x20000
	s_addc_u32 s13, s13, 0
	global_load_dwordx4 v[32:35], v9, s[12:13] nt
	s_add_u32 s12, s12, 0x20000
	s_addc_u32 s13, s13, 0
	global_load_dwordx4 v[36:39], v9, s[12:13] nt
	s_add_u32 s12, s12, 0x20000
	s_addc_u32 s13, s13, 0
	global_load_dwordx4 v[40:43], v9, s[12:13] nt
	s_add_u32 s12, s12, 0x20000
	s_addc_u32 s13, s13, 0
	global_load_dwordx4 v[44:47], v9, s[12:13] nt
	s_add_u32 s12, s12, 0x20000
	s_addc_u32 s13, s13, 0
	global_load_dwordx4 v[48:51], v9, s[12:13] nt
	s_add_u32 s12, s12, 0x20000
	s_addc_u32 s13, s13, 0
	global_load_dwordx4 v[52:55], v9, s[12:13] nt
	s_add_u32 s12, s12, 0x20000
	s_addc_u32 s13, s13, 0
	global_load_dwordx4 v[56:59], v9, s[12:13] nt
	s_add_u32 s12, s12, 0x20000
	s_addc_u32 s13, s13, 0
	global_load_dwordx4 v[60:63], v9, s[12:13] nt
	s_add_u32 s12, s12, 0x20000
	s_addc_u32 s13, s13, 0
	global_load_dwordx4 v[64:67], v9, s[12:13] nt
	s_add_u32 s12, s12, 0x20000
	s_addc_u32 s13, s13, 0
	global_load_dwordx4 v[68:71], v9, s[12:13] nt
	s_add_u32 s12, s12, 0x20000
	s_addc_u32 s13, s13, 0
	global_load_dwordx4 v[72:75], v9, s[12:13] nt
	s_add_u32 s12, s12, 0x20000
	s_addc_u32 s13, s13, 0
	global_load_dwordx4 v[76:79], v9, s[12:13] nt
	s_add_u32 s12, s12, 0x20000
	s_addc_u32 s13, s13, 0
	global_load_dwordx4 v[80:83], v9, s[12:13] nt
	s_add_u32 s12, s12, 0x20000
	s_addc_u32 s13, s13, 0
	global_load_dwordx4 v[84:87], v9, s[12:13] nt
	v_and_b32_e32 v13, 3, v13
	v_cvt_f32_ubyte0_e32 v13, v13
	v_sub_f32_e32 v13, 0xc0a00000, v13
	v_exp_f32_e32 v13, v13
	s_nop 0
	v_sub_f32_e32 v13, 1.0, v13
	v_log_f32_e32 v13, v13
	s_nop 0
	v_mul_f32_e32 v13, 0x43800000, v13
	v_exp_f32_e32 v8, v13
	s_add_u32 s14, s26, 0x27400000
	s_addc_u32 s15, s27, 0
	s_add_u32 s6, s24, 0x82c4000
	s_addc_u32 s7, s25, 0
	v_mov_b32_e32 v0, 0
	v_mov_b32_e32 v1, 0
	v_mov_b32_e32 v2, 0
	v_mov_b32_e32 v3, 0
	v_mov_b32_e32 v4, 0
	v_mov_b32_e32 v5, 0
	v_mov_b32_e32 v6, 0
	v_mov_b32_e32 v7, 0
	v_cvt_pk_bf16_f32 v88, v0, v1
	v_cvt_pk_bf16_f32 v89, v2, v3
	v_cvt_pk_bf16_f32 v90, v4, v5
	v_cvt_pk_bf16_f32 v91, v6, v7
	global_store_dwordx4 v10, v[88:91], s[14:15]
	s_add_u32 s14, s14, 0x40000
	s_addc_u32 s15, s15, 0
	s_waitcnt vmcnt(16)
	v_lshlrev_b32_e32 v16, 16, v24
	v_and_b32_e32 v17, 0xffff0000, v24
	v_lshlrev_b32_e32 v18, 16, v25
	v_and_b32_e32 v19, 0xffff0000, v25
	v_lshlrev_b32_e32 v20, 16, v26
	v_and_b32_e32 v21, 0xffff0000, v26
	v_lshlrev_b32_e32 v22, 16, v27
	v_and_b32_e32 v23, 0xffff0000, v27
	v_fma_f32 v0, v8, v0, v16
	v_fma_f32 v1, v8, v1, v17
	v_fma_f32 v2, v8, v2, v18
	v_fma_f32 v3, v8, v3, v19
	v_fma_f32 v4, v8, v4, v20
	v_fma_f32 v5, v8, v5, v21
	v_fma_f32 v6, v8, v6, v22
	v_fma_f32 v7, v8, v7, v23
	v_cvt_pk_bf16_f32 v24, v0, v1
	v_cvt_pk_bf16_f32 v25, v2, v3
	v_cvt_pk_bf16_f32 v26, v4, v5
	v_cvt_pk_bf16_f32 v27, v6, v7
	global_store_dwordx4 v10, v[24:27], s[14:15]
	s_add_u32 s14, s14, 0x40000
	s_addc_u32 s15, s15, 0
	s_waitcnt vmcnt(16)
	v_lshlrev_b32_e32 v16, 16, v28
	v_and_b32_e32 v17, 0xffff0000, v28
	v_lshlrev_b32_e32 v18, 16, v29
	v_and_b32_e32 v19, 0xffff0000, v29
	v_lshlrev_b32_e32 v20, 16, v30
	v_and_b32_e32 v21, 0xffff0000, v30
	v_lshlrev_b32_e32 v22, 16, v31
	v_and_b32_e32 v23, 0xffff0000, v31
	v_fma_f32 v0, v8, v0, v16
	v_fma_f32 v1, v8, v1, v17
	v_fma_f32 v2, v8, v2, v18
	v_fma_f32 v3, v8, v3, v19
	v_fma_f32 v4, v8, v4, v20
	v_fma_f32 v5, v8, v5, v21
	v_fma_f32 v6, v8, v6, v22
	v_fma_f32 v7, v8, v7, v23
	v_cvt_pk_bf16_f32 v28, v0, v1
	v_cvt_pk_bf16_f32 v29, v2, v3
	v_cvt_pk_bf16_f32 v30, v4, v5
	v_cvt_pk_bf16_f32 v31, v6, v7
	global_store_dwordx4 v10, v[28:31], s[14:15]
	s_add_u32 s14, s14, 0x40000
	s_addc_u32 s15, s15, 0
	s_waitcnt vmcnt(16)
	v_lshlrev_b32_e32 v16, 16, v32
	v_and_b32_e32 v17, 0xffff0000, v32
	v_lshlrev_b32_e32 v18, 16, v33
	v_and_b32_e32 v19, 0xffff0000, v33
	v_lshlrev_b32_e32 v20, 16, v34
	v_and_b32_e32 v21, 0xffff0000, v34
	v_lshlrev_b32_e32 v22, 16, v35
	v_and_b32_e32 v23, 0xffff0000, v35
	v_fma_f32 v0, v8, v0, v16
	v_fma_f32 v1, v8, v1, v17
	v_fma_f32 v2, v8, v2, v18
	v_fma_f32 v3, v8, v3, v19
	v_fma_f32 v4, v8, v4, v20
	v_fma_f32 v5, v8, v5, v21
	v_fma_f32 v6, v8, v6, v22
	v_fma_f32 v7, v8, v7, v23
	v_cvt_pk_bf16_f32 v32, v0, v1
	v_cvt_pk_bf16_f32 v33, v2, v3
	v_cvt_pk_bf16_f32 v34, v4, v5
	v_cvt_pk_bf16_f32 v35, v6, v7
	global_store_dwordx4 v10, v[32:35], s[14:15]
	s_add_u32 s14, s14, 0x40000
	s_addc_u32 s15, s15, 0
	s_waitcnt vmcnt(16)
	v_lshlrev_b32_e32 v16, 16, v36
	v_and_b32_e32 v17, 0xffff0000, v36
	v_lshlrev_b32_e32 v18, 16, v37
	v_and_b32_e32 v19, 0xffff0000, v37
	v_lshlrev_b32_e32 v20, 16, v38
	v_and_b32_e32 v21, 0xffff0000, v38
	v_lshlrev_b32_e32 v22, 16, v39
	v_and_b32_e32 v23, 0xffff0000, v39
	v_fma_f32 v0, v8, v0, v16
	v_fma_f32 v1, v8, v1, v17
	v_fma_f32 v2, v8, v2, v18
	v_fma_f32 v3, v8, v3, v19
	v_fma_f32 v4, v8, v4, v20
	v_fma_f32 v5, v8, v5, v21
	v_fma_f32 v6, v8, v6, v22
	v_fma_f32 v7, v8, v7, v23
	v_cvt_pk_bf16_f32 v36, v0, v1
	v_cvt_pk_bf16_f32 v37, v2, v3
	v_cvt_pk_bf16_f32 v38, v4, v5
	v_cvt_pk_bf16_f32 v39, v6, v7
	global_store_dwordx4 v10, v[36:39], s[14:15]
	s_add_u32 s14, s14, 0x40000
	s_addc_u32 s15, s15, 0
	s_waitcnt vmcnt(16)
; DI void unpack8(const u32x4 w, float (&f)[8]) { f[0] = bflo(w.x); f[1] = bfhi(w.x); f[2] = bflo(w.y); f[3] = bfhi(w.y); f[4] = bflo(w.z); f[5] = bfhi(w.z); f[6] = bflo(w.w); f[7] = bfhi(w.w); }
; DI u32x4 pack8(const float (&f)[8]) { u32x4 w; w.x = pk2(f[0], f[1]); w.y = pk2(f[2], f[3]); w.z = pk2(f[4], f[5]); w.w = pk2(f[6], f[7]); return w; }
; DI void phase8(const Params& p, LAS unsigned char* lds) {
;     ...
; #pragma unroll
;         for (int c = 0; c < 16; ++c) {
;             const size_t u = (size_t)(bh * 16 + c);
;             float kv[8]; unpack8(__builtin_nontemporal_load((const u32x4*)(KVC + u * 65536 + e)), kv);
;             *(u32x4*)(BSV + (u * 256 + dv) * 512 + dk0) = pack8(s);
; #pragma unroll
;             for (int k = 0; k < 8; ++k) s[k] = g256 * s[k] + kv[k];
;         }
	v_lshlrev_b32_e32 v16, 16, v40
	v_and_b32_e32 v17, 0xffff0000, v40
	v_lshlrev_b32_e32 v18, 16, v41
	v_and_b32_e32 v19, 0xffff0000, v41
	v_lshlrev_b32_e32 v20, 16, v42
	v_and_b32_e32 v21, 0xffff0000, v42
	v_lshlrev_b32_e32 v22, 16, v43
	v_and_b32_e32 v23, 0xffff0000, v43
	v_fma_f32 v0, v8, v0, v16
	v_fma_f32 v1, v8, v1, v17
	v_fma_f32 v2, v8, v2, v18
	v_fma_f32 v3, v8, v3, v19
	v_fma_f32 v4, v8, v4, v20
	v_fma_f32 v5, v8, v5, v21
	v_fma_f32 v6, v8, v6, v22
	v_fma_f32 v7, v8, v7, v23
	v_cvt_pk_bf16_f32 v40, v0, v1
	v_cvt_pk_bf16_f32 v41, v2, v3
	v_cvt_pk_bf16_f32 v42, v4, v5
	v_cvt_pk_bf16_f32 v43, v6, v7
	global_store_dwordx4 v10, v[40:43], s[14:15]
	s_add_u32 s14, s14, 0x40000
	s_addc_u32 s15, s15, 0
	s_waitcnt vmcnt(16)
	v_lshlrev_b32_e32 v16, 16, v44
	v_and_b32_e32 v17, 0xffff0000, v44
	v_lshlrev_b32_e32 v18, 16, v45
	v_and_b32_e32 v19, 0xffff0000, v45
	v_lshlrev_b32_e32 v20, 16, v46
	v_and_b32_e32 v21, 0xffff0000, v46
	v_lshlrev_b32_e32 v22, 16, v47
	v_and_b32_e32 v23, 0xffff0000, v47
	v_fma_f32 v0, v8, v0, v16
	v_fma_f32 v1, v8, v1, v17
	v_fma_f32 v2, v8, v2, v18
	v_fma_f32 v3, v8, v3, v19
	v_fma_f32 v4, v8, v4, v20
	v_fma_f32 v5, v8, v5, v21
	v_fma_f32 v6, v8, v6, v22
	v_fma_f32 v7, v8, v7, v23
	v_cvt_pk_bf16_f32 v44, v0, v1
	v_cvt_pk_bf16_f32 v45, v2, v3
	v_cvt_pk_bf16_f32 v46, v4, v5
	v_cvt_pk_bf16_f32 v47, v6, v7
	global_store_dwordx4 v10, v[44:47], s[14:15]
	s_add_u32 s14, s14, 0x40000
	s_addc_u32 s15, s15, 0
	s_waitcnt vmcnt(16)
	v_lshlrev_b32_e32 v16, 16, v48
	v_and_b32_e32 v17, 0xffff0000, v48
	v_lshlrev_b32_e32 v18, 16, v49
	v_and_b32_e32 v19, 0xffff0000, v49
	v_lshlrev_b32_e32 v20, 16, v50
	v_and_b32_e32 v21, 0xffff0000, v50
	v_lshlrev_b32_e32 v22, 16, v51
	v_and_b32_e32 v23, 0xffff0000, v51
	v_fma_f32 v0, v8, v0, v16
	v_fma_f32 v1, v8, v1, v17
	v_fma_f32 v2, v8, v2, v18
	v_fma_f32 v3, v8, v3, v19
	v_fma_f32 v4, v8, v4, v20
	v_fma_f32 v5, v8, v5, v21
	v_fma_f32 v6, v8, v6, v22
	v_fma_f32 v7, v8, v7, v23
	v_cvt_pk_bf16_f32 v48, v0, v1
	v_cvt_pk_bf16_f32 v49, v2, v3
	v_cvt_pk_bf16_f32 v50, v4, v5
	v_cvt_pk_bf16_f32 v51, v6, v7
	global_store_dwordx4 v10, v[48:51], s[14:15]
	s_add_u32 s14, s14, 0x40000
	s_addc_u32 s15, s15, 0
	s_waitcnt vmcnt(16)
	v_lshlrev_b32_e32 v16, 16, v52
	v_and_b32_e32 v17, 0xffff0000, v52
	v_lshlrev_b32_e32 v18, 16, v53
	v_and_b32_e32 v19, 0xffff0000, v53
	v_lshlrev_b32_e32 v20, 16, v54
	v_and_b32_e32 v21, 0xffff0000, v54
	v_lshlrev_b32_e32 v22, 16, v55
	v_and_b32_e32 v23, 0xffff0000, v55
	v_fma_f32 v0, v8, v0, v16
	v_fma_f32 v1, v8, v1, v17
	v_fma_f32 v2, v8, v2, v18
	v_fma_f32 v3, v8, v3, v19
	v_fma_f32 v4, v8, v4, v20
	v_fma_f32 v5, v8, v5, v21
	v_fma_f32 v6, v8, v6, v22
	v_fma_f32 v7, v8, v7, v23
	v_cvt_pk_bf16_f32 v52, v0, v1
	v_cvt_pk_bf16_f32 v53, v2, v3
	v_cvt_pk_bf16_f32 v54, v4, v5
	v_cvt_pk_bf16_f32 v55, v6, v7
	global_store_dwordx4 v10, v[52:55], s[14:15]
	s_add_u32 s14, s14, 0x40000
	s_addc_u32 s15, s15, 0
	s_waitcnt vmcnt(16)
	v_lshlrev_b32_e32 v16, 16, v56
	v_and_b32_e32 v17, 0xffff0000, v56
	v_lshlrev_b32_e32 v18, 16, v57
	v_and_b32_e32 v19, 0xffff0000, v57
	v_lshlrev_b32_e32 v20, 16, v58
	v_and_b32_e32 v21, 0xffff0000, v58
	v_lshlrev_b32_e32 v22, 16, v59
	v_and_b32_e32 v23, 0xffff0000, v59
	v_fma_f32 v0, v8, v0, v16
	v_fma_f32 v1, v8, v1, v17
	v_fma_f32 v2, v8, v2, v18
	v_fma_f32 v3, v8, v3, v19
	v_fma_f32 v4, v8, v4, v20
	v_fma_f32 v5, v8, v5, v21
	v_fma_f32 v6, v8, v6, v22
	v_fma_f32 v7, v8, v7, v23
	v_cvt_pk_bf16_f32 v56, v0, v1
	v_cvt_pk_bf16_f32 v57, v2, v3
	v_cvt_pk_bf16_f32 v58, v4, v5
	v_cvt_pk_bf16_f32 v59, v6, v7
	global_store_dwordx4 v10, v[56:59], s[14:15]
	s_add_u32 s14, s14, 0x40000
	s_addc_u32 s15, s15, 0
	s_waitcnt vmcnt(16)
	v_lshlrev_b32_e32 v16, 16, v60
	v_and_b32_e32 v17, 0xffff0000, v60
	v_lshlrev_b32_e32 v18, 16, v61
	v_and_b32_e32 v19, 0xffff0000, v61
	v_lshlrev_b32_e32 v20, 16, v62
	v_and_b32_e32 v21, 0xffff0000, v62
	v_lshlrev_b32_e32 v22, 16, v63
	v_and_b32_e32 v23, 0xffff0000, v63
	v_fma_f32 v0, v8, v0, v16
	v_fma_f32 v1, v8, v1, v17
	v_fma_f32 v2, v8, v2, v18
	v_fma_f32 v3, v8, v3, v19
	v_fma_f32 v4, v8, v4, v20
	v_fma_f32 v5, v8, v5, v21
	v_fma_f32 v6, v8, v6, v22
	v_fma_f32 v7, v8, v7, v23
	v_cvt_pk_bf16_f32 v60, v0, v1
	v_cvt_pk_bf16_f32 v61, v2, v3
	v_cvt_pk_bf16_f32 v62, v4, v5
	v_cvt_pk_bf16_f32 v63, v6, v7
	global_store_dwordx4 v10, v[60:63], s[14:15]
	s_add_u32 s14, s14, 0x40000
	s_addc_u32 s15, s15, 0
	s_waitcnt vmcnt(16)
	v_lshlrev_b32_e32 v16, 16, v64
	v_and_b32_e32 v17, 0xffff0000, v64
	v_lshlrev_b32_e32 v18, 16, v65
	v_and_b32_e32 v19, 0xffff0000, v65
	v_lshlrev_b32_e32 v20, 16, v66
	v_and_b32_e32 v21, 0xffff0000, v66
	v_lshlrev_b32_e32 v22, 16, v67
	v_and_b32_e32 v23, 0xffff0000, v67
	v_fma_f32 v0, v8, v0, v16
	v_fma_f32 v1, v8, v1, v17
	v_fma_f32 v2, v8, v2, v18
	v_fma_f32 v3, v8, v3, v19
	v_fma_f32 v4, v8, v4, v20
	v_fma_f32 v5, v8, v5, v21
	v_fma_f32 v6, v8, v6, v22
	v_fma_f32 v7, v8, v7, v23
	v_cvt_pk_bf16_f32 v64, v0, v1
	v_cvt_pk_bf16_f32 v65, v2, v3
	v_cvt_pk_bf16_f32 v66, v4, v5
	v_cvt_pk_bf16_f32 v67, v6, v7
	global_store_dwordx4 v10, v[64:67], s[14:15]
	s_add_u32 s14, s14, 0x40000
	s_addc_u32 s15, s15, 0
	s_waitcnt vmcnt(16)
; DI void unpack8(const u32x4 w, float (&f)[8]) { f[0] = bflo(w.x); f[1] = bfhi(w.x); f[2] = bflo(w.y); f[3] = bfhi(w.y); f[4] = bflo(w.z); f[5] = bfhi(w.z); f[6] = bflo(w.w); f[7] = bfhi(w.w); }
; DI u32x4 pack8(const float (&f)[8]) { u32x4 w; w.x = pk2(f[0], f[1]); w.y = pk2(f[2], f[3]); w.z = pk2(f[4], f[5]); w.w = pk2(f[6], f[7]); return w; }
; DI void phase8(const Params& p, LAS unsigned char* lds) {
;     ...
; #pragma unroll
;         for (int c = 0; c < 16; ++c) {
;             const size_t u = (size_t)(bh * 16 + c);
;             float kv[8]; unpack8(__builtin_nontemporal_load((const u32x4*)(KVC + u * 65536 + e)), kv);
;             *(u32x4*)(BSV + (u * 256 + dv) * 512 + dk0) = pack8(s);
; #pragma unroll
;             for (int k = 0; k < 8; ++k) s[k] = g256 * s[k] + kv[k];
;         }
;         float* o = p.out + O_RETP + (size_t)bh * 65536 + (size_t)dk0 * 256 + dv;
; #pragma unroll
;         for (int k = 0; k < 8; ++k) __builtin_nontemporal_store(s[k], o + (size_t)k * 256);
	v_lshlrev_b32_e32 v16, 16, v68
	v_and_b32_e32 v17, 0xffff0000, v68
	v_lshlrev_b32_e32 v18, 16, v69
	v_and_b32_e32 v19, 0xffff0000, v69
	v_lshlrev_b32_e32 v20, 16, v70
	v_and_b32_e32 v21, 0xffff0000, v70
	v_lshlrev_b32_e32 v22, 16, v71
	v_and_b32_e32 v23, 0xffff0000, v71
	v_fma_f32 v0, v8, v0, v16
	v_fma_f32 v1, v8, v1, v17
	v_fma_f32 v2, v8, v2, v18
	v_fma_f32 v3, v8, v3, v19
	v_fma_f32 v4, v8, v4, v20
	v_fma_f32 v5, v8, v5, v21
	v_fma_f32 v6, v8, v6, v22
	v_fma_f32 v7, v8, v7, v23
	v_cvt_pk_bf16_f32 v68, v0, v1
	v_cvt_pk_bf16_f32 v69, v2, v3
	v_cvt_pk_bf16_f32 v70, v4, v5
	v_cvt_pk_bf16_f32 v71, v6, v7
	global_store_dwordx4 v10, v[68:71], s[14:15]
	s_add_u32 s14, s14, 0x40000
	s_addc_u32 s15, s15, 0
	s_waitcnt vmcnt(16)
	v_lshlrev_b32_e32 v16, 16, v72
	v_and_b32_e32 v17, 0xffff0000, v72
	v_lshlrev_b32_e32 v18, 16, v73
	v_and_b32_e32 v19, 0xffff0000, v73
	v_lshlrev_b32_e32 v20, 16, v74
	v_and_b32_e32 v21, 0xffff0000, v74
	v_lshlrev_b32_e32 v22, 16, v75
	v_and_b32_e32 v23, 0xffff0000, v75
	v_fma_f32 v0, v8, v0, v16
	v_fma_f32 v1, v8, v1, v17
	v_fma_f32 v2, v8, v2, v18
	v_fma_f32 v3, v8, v3, v19
	v_fma_f32 v4, v8, v4, v20
	v_fma_f32 v5, v8, v5, v21
	v_fma_f32 v6, v8, v6, v22
	v_fma_f32 v7, v8, v7, v23
	v_cvt_pk_bf16_f32 v72, v0, v1
	v_cvt_pk_bf16_f32 v73, v2, v3
	v_cvt_pk_bf16_f32 v74, v4, v5
	v_cvt_pk_bf16_f32 v75, v6, v7
	global_store_dwordx4 v10, v[72:75], s[14:15]
	s_add_u32 s14, s14, 0x40000
	s_addc_u32 s15, s15, 0
	s_waitcnt vmcnt(16)
	v_lshlrev_b32_e32 v16, 16, v76
	v_and_b32_e32 v17, 0xffff0000, v76
	v_lshlrev_b32_e32 v18, 16, v77
	v_and_b32_e32 v19, 0xffff0000, v77
	v_lshlrev_b32_e32 v20, 16, v78
	v_and_b32_e32 v21, 0xffff0000, v78
	v_lshlrev_b32_e32 v22, 16, v79
	v_and_b32_e32 v23, 0xffff0000, v79
	v_fma_f32 v0, v8, v0, v16
	v_fma_f32 v1, v8, v1, v17
	v_fma_f32 v2, v8, v2, v18
	v_fma_f32 v3, v8, v3, v19
	v_fma_f32 v4, v8, v4, v20
	v_fma_f32 v5, v8, v5, v21
	v_fma_f32 v6, v8, v6, v22
	v_fma_f32 v7, v8, v7, v23
	v_cvt_pk_bf16_f32 v76, v0, v1
	v_cvt_pk_bf16_f32 v77, v2, v3
	v_cvt_pk_bf16_f32 v78, v4, v5
	v_cvt_pk_bf16_f32 v79, v6, v7
	global_store_dwordx4 v10, v[76:79], s[14:15]
	s_add_u32 s14, s14, 0x40000
	s_addc_u32 s15, s15, 0
	s_waitcnt vmcnt(16)
	v_lshlrev_b32_e32 v16, 16, v80
	v_and_b32_e32 v17, 0xffff0000, v80
	v_lshlrev_b32_e32 v18, 16, v81
	v_and_b32_e32 v19, 0xffff0000, v81
	v_lshlrev_b32_e32 v20, 16, v82
	v_and_b32_e32 v21, 0xffff0000, v82
	v_lshlrev_b32_e32 v22, 16, v83
	v_and_b32_e32 v23, 0xffff0000, v83
	v_fma_f32 v0, v8, v0, v16
	v_fma_f32 v1, v8, v1, v17
	v_fma_f32 v2, v8, v2, v18
	v_fma_f32 v3, v8, v3, v19
	v_fma_f32 v4, v8, v4, v20
	v_fma_f32 v5, v8, v5, v21
	v_fma_f32 v6, v8, v6, v22
	v_fma_f32 v7, v8, v7, v23
	v_cvt_pk_bf16_f32 v80, v0, v1
	v_cvt_pk_bf16_f32 v81, v2, v3
	v_cvt_pk_bf16_f32 v82, v4, v5
	v_cvt_pk_bf16_f32 v83, v6, v7
	global_store_dwordx4 v10, v[80:83], s[14:15]
	s_waitcnt vmcnt(16)
	v_lshlrev_b32_e32 v16, 16, v84
	v_and_b32_e32 v17, 0xffff0000, v84
	v_lshlrev_b32_e32 v18, 16, v85
	v_and_b32_e32 v19, 0xffff0000, v85
	v_lshlrev_b32_e32 v20, 16, v86
	v_and_b32_e32 v21, 0xffff0000, v86
	v_lshlrev_b32_e32 v22, 16, v87
	v_and_b32_e32 v23, 0xffff0000, v87
	v_fma_f32 v0, v8, v0, v16
	v_fma_f32 v1, v8, v1, v17
	v_fma_f32 v2, v8, v2, v18
	v_fma_f32 v3, v8, v3, v19
	v_fma_f32 v4, v8, v4, v20
	v_fma_f32 v5, v8, v5, v21
	v_fma_f32 v6, v8, v6, v22
	v_fma_f32 v7, v8, v7, v23
	v_lshrrev_b32_e32 v13, 5, v226
	v_and_b32_e32 v14, 31, v226
	v_mul_u32_u24_e32 v13, 0x404, v13
	v_lshl_add_u32 v13, v14, 5, v13
	ds_write_b32 v13, v0
	ds_write_b32 v13, v1 offset:4
	ds_write_b32 v13, v2 offset:8
	ds_write_b32 v13, v3 offset:12
	ds_write_b32 v13, v4 offset:16
	ds_write_b32 v13, v5 offset:20
	ds_write_b32 v13, v6 offset:24
	ds_write_b32 v13, v7 offset:28
	v_and_b32_e32 v14, 3, v226
	v_lshrrev_b32_e32 v15, 2, v226
	v_lshlrev_b32_e32 v12, 4, v14
	v_lshl_add_u32 v12, v15, 10, v12
	v_mul_u32_u24_e32 v14, 0x1010, v14
	v_lshl_add_u32 v14, v15, 2, v14
	v_add_u32_e32 v11, 0x20000, v12
	s_lshr_b32 s14, s2, 4
	s_lshl_b32 s14, s14, 18
	s_and_b32 s15, s2, 15
	s_lshl_b32 s15, s15, 6
	s_add_i32 s14, s14, s15
	s_add_u32 s6, s6, s14
	s_addc_u32 s7, s7, 0
	s_waitcnt lgkmcnt(0)
	s_barrier
	ds_read_b32 v16, v14
	ds_read_b32 v17, v14 offset:1028
	ds_read_b32 v18, v14 offset:2056
	ds_read_b32 v19, v14 offset:3084
	ds_read_b32 v20, v14 offset:512
	ds_read_b32 v21, v14 offset:1540
	ds_read_b32 v22, v14 offset:2568
	ds_read_b32 v23, v14 offset:3596
	s_waitcnt lgkmcnt(4)
	global_store_dwordx4 v12, v[16:19], s[6:7] nt
	s_waitcnt lgkmcnt(0)
	global_store_dwordx4 v11, v[20:23], s[6:7] nt
